# phases 5/6 three-way mix: by (blockIdx>>3)&3 a workgroup runs ret_out x4 then conv x2 (0), conv x2 then ret_out x4 (1), or conv item 1, ret_out x4, conv item 2 (2,3), so about a third of the chip is i
# baseline (speedup 1.0000x reference)
.LBB0_899:
	s_mov_b32 s100, 0
	s_cmp_lt_i32 s92, 7
	s_cselect_b64 s[24:25], -1, 0
	s_cmp_gt_i32 s92, 6
	s_cselect_b64 s[0:1], -1, 0
	s_cmp_lt_i32 s93, 7
	s_cselect_b64 s[4:5], -1, 0
	s_or_b64 s[0:1], s[0:1], s[4:5]
	s_and_b64 vcc, exec, s[0:1]
	s_cbranch_vccnz .LBB0_905
	s_cmpk_gt_i32 s20, 0x3ff
	s_cbranch_scc1 .LBB0_905
	s_cmp_lg_u32 s34, 0x100
	s_cbranch_scc1 .Lp6_retout_entry
	s_bfe_u32 s99, s20, 0x20003
	s_cmp_eq_u32 s99, 0
	s_cbranch_scc1 .Lp6_retout_entry
	v_writelane_b32 v254, s54, 0
	v_writelane_b32 v254, s55, 1
	v_writelane_b32 v254, s56, 2
	v_writelane_b32 v254, s57, 3
	s_mov_b32 s100, 1
	s_cmp_eq_u32 s99, 1
	s_cbranch_scc1 .LBB0_905
	s_mov_b32 s100, 3
	s_movk_i32 s34, 0x200
	s_branch .LBB0_905

.LBB0_905:
	s_cmp_eq_u32 s100, 2
	s_cbranch_scc1 .LBB0_945
	s_cmp_lg_u32 s100, 4
	s_cbranch_scc1 .Lp6_conv_go
	s_mov_b32 s100, 5
	s_mov_b32 s101, s20
	s_addk_i32 s20, 0x100
	s_cmp_gt_i32 s93, 5
	s_cselect_b64 s[2:3], -1, 0

.LBB0_945:
	s_cmp_eq_u32 s100, 5
	s_cbranch_scc0 .Lp6_n5
	s_mov_b32 s20, s101
	s_mov_b32 s100, 6
.Lp6_n5:
	s_cmp_eq_u32 s100, 3
	s_cbranch_scc0 .Lp6_n3
	s_movk_i32 s34, 0x100
	s_mov_b32 s100, 4
	s_branch .Lp6_to_retout

.Lp6_to_retout:
	v_readlane_b32 s54, v254, 0
	v_readlane_b32 s55, v254, 1
	v_readlane_b32 s56, v254, 2
	v_readlane_b32 s57, v254, 3
	s_waitcnt vmcnt(0) lgkmcnt(0)
	s_barrier
	s_nop 4
	s_branch .Lp6_retout_entry
